# next unit's As[1][1] half-tile requested at K-loop exit before the epilogue stores; peeled iteration's third wait relaxed too
# speedup vs baseline: 1.0254x; 1.0024x over previous
.Lk_done:
	s_add_u32 s52, s0, 0x80
	s_addc_u32 s53, s1, 0
	v_lshl_add_u64 v[144:145], s[52:53], 0, v[136:137]
	s_add_i32 m0, s9, 0xc000
	global_load_lds_dwordx4 v[144:145], off
	v_lshl_add_u64 v[144:145], s[52:53], 0, v[138:139]
	s_add_i32 m0, s9, 0xe000
	s_nop 0
	global_load_lds_dwordx4 v[144:145], off
	v_readlane_b32 s42, v233, 50
	v_readlane_b32 s43, v233, 51
	s_and_b64 vcc, exec, s[42:43]
	s_cbranch_vccz .LBB0_336
	s_barrier

.Lk_peel:
	s_add_i32 s51, s50, 2
	s_add_u32 s52, s42, 0x80
	s_addc_u32 s53, s43, 0
	s_add_i32 s54, 0, 0x10000
	s_cmp_eq_u32 s87, s50
	s_cselect_b32 s79, s1, s53
	s_cselect_b32 s78, s0, s52
	v_add_u32_e32 v144, s54, v147
	s_cselect_b32 s53, s75, s49
	s_cselect_b32 s52, s74, s48
	s_add_i32 s50, 0, 0x14000
	s_waitcnt lgkmcnt(0)
	ds_read_b128 v[140:143], v144
	ds_read_b128 v[162:165], v144 offset:1024
	ds_read_b128 v[166:169], v144 offset:2048
	ds_read_b128 v[170:173], v144 offset:3072
	v_add_u32_e32 v144, s50, v147
	ds_read_b128 v[174:177], v144
	ds_read_b128 v[178:181], v144 offset:1024
	ds_read_b128 v[182:185], v144 offset:2048
	ds_read_b128 v[186:189], v144 offset:3072
	ds_read_b128 v[190:193], v149
	ds_read_b128 v[194:197], v149 offset:1024
	ds_read_b128 v[198:201], v149 offset:2048
	ds_read_b128 v[202:205], v149 offset:3072
	ds_read_b128 v[206:209], v149 offset:4096
	ds_read_b128 v[210:213], v149 offset:5120
	ds_read_b128 v[214:217], v149 offset:6144
	ds_read_b128 v[218:221], v149 offset:7168
	s_waitcnt vmcnt(16)
	s_waitcnt lgkmcnt(0)
	s_barrier
	s_setprio 1
	s_waitcnt lgkmcnt(0)
	v_mfma_f32_16x16x32_bf16 v[126:129], v[140:143], v[190:193], 0
	v_mfma_f32_16x16x32_bf16 v[122:125], v[166:169], v[190:193], 0
	v_mfma_f32_16x16x32_bf16 v[110:113], v[140:143], v[198:201], 0
	v_mfma_f32_16x16x32_bf16 v[106:109], v[166:169], v[198:201], 0
	v_mfma_f32_16x16x32_bf16 v[92:95], v[140:143], v[206:209], 0
	v_mfma_f32_16x16x32_bf16 v[88:91], v[166:169], v[206:209], 0
	v_mfma_f32_16x16x32_bf16 v[76:79], v[140:143], v[214:217], 0
	v_mfma_f32_16x16x32_bf16 v[72:75], v[166:169], v[214:217], 0
	v_mfma_f32_16x16x32_bf16 v[126:129], v[162:165], v[194:197], v[126:129]
	v_mfma_f32_16x16x32_bf16 v[122:125], v[170:173], v[194:197], v[122:125]
	v_mfma_f32_16x16x32_bf16 v[110:113], v[162:165], v[202:205], v[110:113]
	v_mfma_f32_16x16x32_bf16 v[106:109], v[170:173], v[202:205], v[106:109]
	v_mfma_f32_16x16x32_bf16 v[92:95], v[162:165], v[210:213], v[92:95]
	v_mfma_f32_16x16x32_bf16 v[88:91], v[170:173], v[210:213], v[88:91]
	v_mfma_f32_16x16x32_bf16 v[76:79], v[162:165], v[218:221], v[76:79]
	v_mfma_f32_16x16x32_bf16 v[72:75], v[170:173], v[218:221], v[72:75]
	s_setprio 0
	s_setprio 1
	v_mfma_f32_16x16x32_bf16 v[118:121], v[174:177], v[190:193], 0
	v_mfma_f32_16x16x32_bf16 v[114:117], v[182:185], v[190:193], 0
	v_mfma_f32_16x16x32_bf16 v[102:105], v[174:177], v[198:201], 0
	v_mfma_f32_16x16x32_bf16 v[98:101], v[182:185], v[198:201], 0
	v_mfma_f32_16x16x32_bf16 v[84:87], v[174:177], v[206:209], 0
	v_mfma_f32_16x16x32_bf16 v[80:83], v[182:185], v[206:209], 0
	v_mfma_f32_16x16x32_bf16 v[68:71], v[174:177], v[214:217], 0
	v_mfma_f32_16x16x32_bf16 v[64:67], v[182:185], v[214:217], 0
	v_mfma_f32_16x16x32_bf16 v[118:121], v[178:181], v[194:197], v[118:121]
	v_mfma_f32_16x16x32_bf16 v[114:117], v[186:189], v[194:197], v[114:117]
	v_mfma_f32_16x16x32_bf16 v[102:105], v[178:181], v[202:205], v[102:105]
	v_mfma_f32_16x16x32_bf16 v[98:101], v[186:189], v[202:205], v[98:101]
	v_mfma_f32_16x16x32_bf16 v[84:87], v[178:181], v[210:213], v[84:87]
	v_mfma_f32_16x16x32_bf16 v[80:83], v[186:189], v[210:213], v[80:83]
	v_mfma_f32_16x16x32_bf16 v[68:71], v[178:181], v[218:221], v[68:71]
	v_mfma_f32_16x16x32_bf16 v[64:67], v[186:189], v[218:221], v[64:67]
	s_setprio 0
	s_barrier
	s_add_i32 s54, s54, s8
	v_lshl_add_u64 v[144:145], s[52:53], 0, v[96:97]
	s_mov_b32 m0, s54
	ds_read_b128 v[190:193], v149 offset:16384
	ds_read_b128 v[194:197], v149 offset:17408
	ds_read_b128 v[198:201], v149 offset:18432
	ds_read_b128 v[202:205], v149 offset:19456
	ds_read_b128 v[206:209], v149 offset:20480
	ds_read_b128 v[210:213], v149 offset:21504
	ds_read_b128 v[214:217], v149 offset:22528
	ds_read_b128 v[218:221], v149 offset:23552
	global_load_lds_dwordx4 v[144:145], off
	s_add_i32 m0, s54, 0x2000
	v_lshl_add_u64 v[150:151], s[52:53], 0, v[134:135]
	s_add_u32 s52, s52, s34
	s_addc_u32 s53, s53, s35
	s_add_i32 s50, s50, s8
	global_load_lds_dwordx4 v[150:151], off
	v_lshl_add_u64 v[222:223], s[52:53], 0, v[96:97]
	s_mov_b32 m0, s50
	v_lshl_add_u64 v[224:225], s[52:53], 0, v[134:135]
	global_load_lds_dwordx4 v[222:223], off
	s_add_i32 m0, s50, 0x2000
	v_lshl_add_u64 v[226:227], s[78:79], 0, v[130:131]
	global_load_lds_dwordx4 v[224:225], off
	s_mov_b32 m0, s9
	v_lshl_add_u64 v[228:229], s[78:79], 0, v[132:133]
	global_load_lds_dwordx4 v[226:227], off
	s_mov_b32 m0, s98
	s_nop 0
	global_load_lds_dwordx4 v[228:229], off
	s_waitcnt vmcnt(16)
	s_waitcnt lgkmcnt(0)
	s_barrier
	s_setprio 1
	s_waitcnt lgkmcnt(0)
	v_mfma_f32_16x16x32_bf16 v[60:63], v[140:143], v[190:193], 0
	v_mfma_f32_16x16x32_bf16 v[56:59], v[166:169], v[190:193], 0
	v_mfma_f32_16x16x32_bf16 v[44:47], v[140:143], v[198:201], 0
	v_mfma_f32_16x16x32_bf16 v[40:43], v[166:169], v[198:201], 0
	v_mfma_f32_16x16x32_bf16 v[28:31], v[140:143], v[206:209], 0
	v_mfma_f32_16x16x32_bf16 v[24:27], v[166:169], v[206:209], 0
	v_mfma_f32_16x16x32_bf16 v[12:15], v[140:143], v[214:217], 0
	v_mfma_f32_16x16x32_bf16 v[8:11], v[166:169], v[214:217], 0
	v_mfma_f32_16x16x32_bf16 v[60:63], v[162:165], v[194:197], v[60:63]
	v_mfma_f32_16x16x32_bf16 v[56:59], v[170:173], v[194:197], v[56:59]
	v_mfma_f32_16x16x32_bf16 v[44:47], v[162:165], v[202:205], v[44:47]
	v_mfma_f32_16x16x32_bf16 v[40:43], v[170:173], v[202:205], v[40:43]
	v_mfma_f32_16x16x32_bf16 v[28:31], v[162:165], v[210:213], v[28:31]
	v_mfma_f32_16x16x32_bf16 v[24:27], v[170:173], v[210:213], v[24:27]
	v_mfma_f32_16x16x32_bf16 v[12:15], v[162:165], v[218:221], v[12:15]
	v_mfma_f32_16x16x32_bf16 v[8:11], v[170:173], v[218:221], v[8:11]
	s_setprio 0
	s_setprio 1
	v_mfma_f32_16x16x32_bf16 v[52:55], v[174:177], v[190:193], 0
	v_mfma_f32_16x16x32_bf16 v[48:51], v[182:185], v[190:193], 0
	v_mfma_f32_16x16x32_bf16 v[36:39], v[174:177], v[198:201], 0
	v_mfma_f32_16x16x32_bf16 v[32:35], v[182:185], v[198:201], 0
	v_mfma_f32_16x16x32_bf16 v[20:23], v[174:177], v[206:209], 0
	v_mfma_f32_16x16x32_bf16 v[16:19], v[182:185], v[206:209], 0
	v_mfma_f32_16x16x32_bf16 v[4:7], v[174:177], v[214:217], 0
	v_mfma_f32_16x16x32_bf16 v[0:3], v[182:185], v[214:217], 0
	v_mfma_f32_16x16x32_bf16 v[52:55], v[178:181], v[194:197], v[52:55]
	v_mfma_f32_16x16x32_bf16 v[48:51], v[186:189], v[194:197], v[48:51]
	v_mfma_f32_16x16x32_bf16 v[36:39], v[178:181], v[202:205], v[36:39]
	v_mfma_f32_16x16x32_bf16 v[32:35], v[186:189], v[202:205], v[32:35]
	v_mfma_f32_16x16x32_bf16 v[20:23], v[178:181], v[210:213], v[20:23]
	v_mfma_f32_16x16x32_bf16 v[16:19], v[186:189], v[210:213], v[16:19]
	v_mfma_f32_16x16x32_bf16 v[4:7], v[178:181], v[218:221], v[4:7]
	v_mfma_f32_16x16x32_bf16 v[0:3], v[186:189], v[218:221], v[0:3]
	s_setprio 0
	s_barrier
	s_add_i32 s50, 0, 0x18000
	v_add_u32_e32 v161, s50, v147
	s_add_i32 s54, 0, 0x1c000
	ds_read_b128 v[140:143], v161
	ds_read_b128 v[162:165], v161 offset:1024
	ds_read_b128 v[166:169], v161 offset:2048
	ds_read_b128 v[170:173], v161 offset:3072
	v_add_u32_e32 v161, s54, v147
	ds_read_b128 v[174:177], v161
	ds_read_b128 v[178:181], v161 offset:1024
	ds_read_b128 v[182:185], v161 offset:2048
	ds_read_b128 v[186:189], v161 offset:3072
	s_add_u32 s52, s78, s34
	s_addc_u32 s53, s79, s35
	s_mov_b32 m0, s99
	v_lshl_add_u64 v[230:231], s[52:53], 0, v[130:131]
	ds_read_b128 v[190:193], v149 offset:32768
	ds_read_b128 v[194:197], v149 offset:33792
	ds_read_b128 v[198:201], v149 offset:34816
	ds_read_b128 v[202:205], v149 offset:35840
	ds_read_b128 v[206:209], v149 offset:36864
	ds_read_b128 v[210:213], v149 offset:37888
	ds_read_b128 v[214:217], v149 offset:38912
	ds_read_b128 v[218:221], v149 offset:39936
	global_load_lds_dwordx4 v[230:231], off
	v_lshl_add_u64 v[230:231], s[52:53], 0, v[132:133]
	s_mov_b32 m0, s76
	s_nop 0
	global_load_lds_dwordx4 v[230:231], off
	s_waitcnt vmcnt(16)
	s_waitcnt lgkmcnt(0)
	s_barrier
	s_setprio 1
	s_waitcnt lgkmcnt(0)
	v_mfma_f32_16x16x32_bf16 v[126:129], v[140:143], v[190:193], v[126:129]
	v_mfma_f32_16x16x32_bf16 v[122:125], v[166:169], v[190:193], v[122:125]
	v_mfma_f32_16x16x32_bf16 v[110:113], v[140:143], v[198:201], v[110:113]
	v_mfma_f32_16x16x32_bf16 v[106:109], v[166:169], v[198:201], v[106:109]
	v_mfma_f32_16x16x32_bf16 v[92:95], v[140:143], v[206:209], v[92:95]
	v_mfma_f32_16x16x32_bf16 v[88:91], v[166:169], v[206:209], v[88:91]
	v_mfma_f32_16x16x32_bf16 v[76:79], v[140:143], v[214:217], v[76:79]
	v_mfma_f32_16x16x32_bf16 v[72:75], v[166:169], v[214:217], v[72:75]
	v_mfma_f32_16x16x32_bf16 v[126:129], v[162:165], v[194:197], v[126:129]
	v_mfma_f32_16x16x32_bf16 v[122:125], v[170:173], v[194:197], v[122:125]
	v_mfma_f32_16x16x32_bf16 v[110:113], v[162:165], v[202:205], v[110:113]
	v_mfma_f32_16x16x32_bf16 v[106:109], v[170:173], v[202:205], v[106:109]
	v_mfma_f32_16x16x32_bf16 v[92:95], v[162:165], v[210:213], v[92:95]
	v_mfma_f32_16x16x32_bf16 v[88:91], v[170:173], v[210:213], v[88:91]
	v_mfma_f32_16x16x32_bf16 v[76:79], v[162:165], v[218:221], v[76:79]
	v_mfma_f32_16x16x32_bf16 v[72:75], v[170:173], v[218:221], v[72:75]
	s_setprio 0
	s_setprio 1
	v_mfma_f32_16x16x32_bf16 v[118:121], v[174:177], v[190:193], v[118:121]
	v_mfma_f32_16x16x32_bf16 v[114:117], v[182:185], v[190:193], v[114:117]
	v_mfma_f32_16x16x32_bf16 v[102:105], v[174:177], v[198:201], v[102:105]
	v_mfma_f32_16x16x32_bf16 v[98:101], v[182:185], v[198:201], v[98:101]
	v_mfma_f32_16x16x32_bf16 v[84:87], v[174:177], v[206:209], v[84:87]
	v_mfma_f32_16x16x32_bf16 v[80:83], v[182:185], v[206:209], v[80:83]
	v_mfma_f32_16x16x32_bf16 v[68:71], v[174:177], v[214:217], v[68:71]
	v_mfma_f32_16x16x32_bf16 v[64:67], v[182:185], v[214:217], v[64:67]
	v_mfma_f32_16x16x32_bf16 v[118:121], v[178:181], v[194:197], v[118:121]
	v_mfma_f32_16x16x32_bf16 v[114:117], v[186:189], v[194:197], v[114:117]
	v_mfma_f32_16x16x32_bf16 v[102:105], v[178:181], v[202:205], v[102:105]
	v_mfma_f32_16x16x32_bf16 v[98:101], v[186:189], v[202:205], v[98:101]
	v_mfma_f32_16x16x32_bf16 v[84:87], v[178:181], v[210:213], v[84:87]
	v_mfma_f32_16x16x32_bf16 v[80:83], v[186:189], v[210:213], v[80:83]
	v_mfma_f32_16x16x32_bf16 v[68:71], v[178:181], v[218:221], v[68:71]
	v_mfma_f32_16x16x32_bf16 v[64:67], v[186:189], v[218:221], v[64:67]
	s_setprio 0
	s_barrier
	s_add_i32 s50, s50, s8
	v_lshl_add_u64 v[144:145], v[144:145], 0, s[12:13]
	s_mov_b32 m0, s50
	ds_read_b128 v[190:193], v149 offset:49152
	ds_read_b128 v[194:197], v149 offset:50176
	ds_read_b128 v[198:201], v149 offset:51200
	ds_read_b128 v[202:205], v149 offset:52224
	ds_read_b128 v[206:209], v149 offset:53248
	ds_read_b128 v[210:213], v149 offset:54272
	ds_read_b128 v[214:217], v149 offset:55296
	ds_read_b128 v[218:221], v149 offset:56320
	global_load_lds_dwordx4 v[144:145], off
	v_lshl_add_u64 v[144:145], v[150:151], 0, s[12:13]
	s_add_i32 m0, s50, 0x2000
	s_add_i32 s50, s54, s8
	global_load_lds_dwordx4 v[144:145], off
	v_lshl_add_u64 v[144:145], v[222:223], 0, s[12:13]
	s_mov_b32 m0, s50
	s_nop 0
	global_load_lds_dwordx4 v[144:145], off
	v_lshl_add_u64 v[144:145], v[224:225], 0, s[12:13]
	s_add_i32 m0, s50, 0x2000
	s_nop 0
	global_load_lds_dwordx4 v[144:145], off
	v_lshl_add_u64 v[144:145], v[226:227], 0, s[12:13]
	s_mov_b32 m0, s77
	s_nop 0
	global_load_lds_dwordx4 v[144:145], off
	v_lshl_add_u64 v[144:145], v[228:229], 0, s[12:13]
	s_mov_b32 m0, s86
	s_nop 0
	global_load_lds_dwordx4 v[144:145], off
	s_waitcnt vmcnt(8)
	s_waitcnt lgkmcnt(0)
	s_barrier
	s_setprio 1
	s_waitcnt lgkmcnt(0)
	v_mfma_f32_16x16x32_bf16 v[60:63], v[140:143], v[190:193], v[60:63]
	v_mfma_f32_16x16x32_bf16 v[56:59], v[166:169], v[190:193], v[56:59]
	v_mfma_f32_16x16x32_bf16 v[44:47], v[140:143], v[198:201], v[44:47]
	v_mfma_f32_16x16x32_bf16 v[40:43], v[166:169], v[198:201], v[40:43]
	v_mfma_f32_16x16x32_bf16 v[28:31], v[140:143], v[206:209], v[28:31]
	v_mfma_f32_16x16x32_bf16 v[24:27], v[166:169], v[206:209], v[24:27]
	v_mfma_f32_16x16x32_bf16 v[12:15], v[140:143], v[214:217], v[12:15]
	v_mfma_f32_16x16x32_bf16 v[8:11], v[166:169], v[214:217], v[8:11]
	v_mfma_f32_16x16x32_bf16 v[60:63], v[162:165], v[194:197], v[60:63]
	v_mfma_f32_16x16x32_bf16 v[56:59], v[170:173], v[194:197], v[56:59]
	v_mfma_f32_16x16x32_bf16 v[44:47], v[162:165], v[202:205], v[44:47]
	v_mfma_f32_16x16x32_bf16 v[40:43], v[170:173], v[202:205], v[40:43]
	v_mfma_f32_16x16x32_bf16 v[28:31], v[162:165], v[210:213], v[28:31]
	v_mfma_f32_16x16x32_bf16 v[24:27], v[170:173], v[210:213], v[24:27]
	v_mfma_f32_16x16x32_bf16 v[12:15], v[162:165], v[218:221], v[12:15]
	v_mfma_f32_16x16x32_bf16 v[8:11], v[170:173], v[218:221], v[8:11]
	s_setprio 0
	s_setprio 1
	v_mfma_f32_16x16x32_bf16 v[52:55], v[174:177], v[190:193], v[52:55]
	v_mfma_f32_16x16x32_bf16 v[48:51], v[182:185], v[190:193], v[48:51]
	v_mfma_f32_16x16x32_bf16 v[36:39], v[174:177], v[198:201], v[36:39]
	v_mfma_f32_16x16x32_bf16 v[32:35], v[182:185], v[198:201], v[32:35]
	v_mfma_f32_16x16x32_bf16 v[20:23], v[174:177], v[206:209], v[20:23]
	v_mfma_f32_16x16x32_bf16 v[16:19], v[182:185], v[206:209], v[16:19]
	v_mfma_f32_16x16x32_bf16 v[4:7], v[174:177], v[214:217], v[4:7]
	v_mfma_f32_16x16x32_bf16 v[0:3], v[182:185], v[214:217], v[0:3]
	v_mfma_f32_16x16x32_bf16 v[52:55], v[178:181], v[194:197], v[52:55]
	v_mfma_f32_16x16x32_bf16 v[48:51], v[186:189], v[194:197], v[48:51]
	v_mfma_f32_16x16x32_bf16 v[36:39], v[178:181], v[202:205], v[36:39]
	v_mfma_f32_16x16x32_bf16 v[32:35], v[186:189], v[202:205], v[32:35]
	v_mfma_f32_16x16x32_bf16 v[20:23], v[178:181], v[210:213], v[20:23]
	v_mfma_f32_16x16x32_bf16 v[16:19], v[186:189], v[210:213], v[16:19]
	v_mfma_f32_16x16x32_bf16 v[4:7], v[178:181], v[218:221], v[4:7]
	v_mfma_f32_16x16x32_bf16 v[0:3], v[186:189], v[218:221], v[0:3]
	s_setprio 0
	s_barrier
	s_add_u32 s42, s42, 0x100
	s_addc_u32 s43, s43, 0
	s_add_u32 s48, s48, 0x100
	s_addc_u32 s49, s49, 0
	s_cmp_ge_u32 s51, s64
	s_mov_b32 s50, s51
	s_cbranch_scc0 .LBB0_333
	s_branch .Lk_done
